# v75 + prep tail rebalance 2: c1/c2 tiles on workgroups 128-255 (fewer transpose rounds) instead of 0-127, compress-bias tiles on 240-255
# baseline (speedup 1.0000x reference)
; DI bf16_t f2bf(float a) { return (bf16_t)(pack2(a, 0.f) & 0xffffu); }
; DI float bf2f(bf16_t b) { return __uint_as_float(((unsigned)b) << 16); }
; DI void phase_prep(const Params& P, unsigned char* smem, int L, int G) {
;     ...
;     float* red = (float*)smem;
;     float* c1 = (float*)(ws + OFF_C1); float* c2 = (float*)(ws + OFF_C2);
;     for (int t = L; t < 128; t += G) {
;       const int i = t >> 5, n0 = (t & 31) * 32;
;       const int kp = tid >> 5, nn = tid & 31;
;       const float* W = P.pe_gate + (size_t)i * 1024 * 1024;
;       const float* g = P.ln_g + i * 1024; const float* bb = P.ln_b + i * 1024;
;       float s1 = 0.f, s2 = 0.f;
;       for (int k = kp * 64; k < kp * 64 + 64; ++k) {
;         const float wv = W[(size_t)k * 1024 + n0 + nn];
;         s1 += bf2f(f2bf(g[k] * wv)); s2 += bb[k] * wv;
;       }
;       __syncthreads();
;       red[kp * 32 + nn] = s1; red[512 + kp * 32 + nn] = s2;
;       __syncthreads();
;       if (tid < 32) {
;         float a = 0.f, b2 = 0.f;
;         for (int q = 0; q < 16; ++q) { a += red[q * 32 + tid]; b2 += red[512 + q * 32 + tid]; }
;         c1[i * 1024 + n0 + tid] = a; c2[i * 1024 + n0 + tid] = b2;
;       }
;     }
.LBB0_153:
	s_add_u32 s10, s72, 0x2b60000
	s_addc_u32 s11, s73, 0
	s_add_u32 s20, s72, 0x2b64000
	s_addc_u32 s21, s73, 0
	s_cmp_ge_u32 s74, 0x100
	s_cselect_b32 s99, 0x80, 0
	s_sub_i32 s98, s70, s99
	s_cmp_lt_u32 s98, 0x80
	s_cselect_b64 vcc, 0, -1
	s_and_b64 vcc, exec, vcc
	v_lshlrev_b32_e32 v1, 2, v0
	v_cmp_gt_i32_e64 s[0:1], 32, v0
	s_barrier
	s_cbranch_vccnz .LBB0_160
	v_lshlrev_b32_e32 v2, 1, v0
	v_and_b32_e32 v6, 0xffffffc0, v2
	v_ashrrev_i32_e32 v7, 31, v6
	v_and_b32_e32 v8, 0x7c, v1
	v_add_u32_e32 v18, -1, v6
	v_lshlrev_b64 v[4:5], 2, v[6:7]
	v_readlane_b32 s36, v246, 1
	v_lshlrev_b64 v[6:7], 12, v[6:7]
	v_and_b32_e32 v3, 0x3fffffe0, v0
	v_readlane_b32 s44, v246, 9
	v_readlane_b32 s45, v246, 10
	v_readlane_b32 s46, v246, 11
	v_readlane_b32 s47, v246, 12
	v_readlane_b32 s48, v246, 13
	v_readlane_b32 s49, v246, 14
	v_or_b32_e32 v6, v6, v8
	v_lshl_or_b32 v16, v3, 2, v8
	v_or_b32_e32 v17, 63, v2
	v_lshl_add_u64 v[2:3], s[44:45], 0, v[4:5]
	v_lshl_add_u64 v[4:5], s[46:47], 0, v[4:5]
	v_lshl_add_u64 v[6:7], s[48:49], 0, v[6:7]
	s_lshl_b32 s33, s98, 5
	s_lshl_b32 s34, s74, 5
	s_mov_b64 s[2:3], 0x1000
	v_add_u32_e32 v19, 0x800, v1
	v_add_u32_e32 v20, 0x400, v1
	v_add_u32_e32 v21, 0xc00, v1
	s_mov_b32 s35, s98
	v_readlane_b32 s37, v246, 2
	v_readlane_b32 s38, v246, 3
	v_readlane_b32 s39, v246, 4
	v_readlane_b32 s40, v246, 5
	v_readlane_b32 s41, v246, 6
	v_readlane_b32 s42, v246, 7
	v_readlane_b32 s43, v246, 8
	v_readlane_b32 s50, v246, 15
	v_readlane_b32 s51, v246, 16
	s_branch .LBB0_156

; DI void phase_prep(const Params& P, unsigned char* smem, int L, int G) {
;     ...
;     for (int t = L; t < 16; t += G) {
;       const int which = t >> 3, n0 = (t & 7) * 32;
;       const int kp = tid >> 5, nn = tid & 31;
;       const float* W = which ? P.l2_phi_v1 : P.l2_phi_k1;
;       float s1 = 0.f;
;       for (int k = kp * 128; k < kp * 128 + 128; ++k) s1 += P.l2_cmp_pos[k] * W[(size_t)k * 256 + n0 + nn];
;       __syncthreads();
;       red[kp * 32 + nn] = s1;
;       __syncthreads();
;       if (tid < 32) { float a = 0.f; for (int q = 0; q < 16; ++q) a += red[q * 32 + tid]; bias[which * 256 + n0 + tid] = a; }
;     }
.LBB0_160:
	s_add_u32 s6, s72, 0x2b68000
	s_addc_u32 s7, s73, 0
	s_cmp_ge_u32 s74, 0x100
	s_cselect_b32 s99, 0xf0, 0
	s_sub_i32 s98, s70, s99
	s_cmp_lt_u32 s98, 16
	s_cselect_b64 s[30:31], -1, 0
	s_andn2_b64 vcc, exec, s[30:31]
	s_barrier
	s_cbranch_vccnz .LBB0_167
	v_and_b32_e32 v4, 0xffffff80, v1
	v_mov_b32_e32 v2, s80
	v_mov_b32_e32 v3, s81
	v_ashrrev_i32_e32 v5, 31, v4
	v_and_b32_e32 v6, 31, v0
	v_add_u32_e32 v11, -1, v4
	v_lshl_add_u64 v[2:3], v[4:5], 2, v[2:3]
	v_lshlrev_b64 v[4:5], 10, v[4:5]
	v_cmp_gt_i32_e32 vcc, 32, v0
	v_or_b32_e32 v10, 0x7f, v1
	v_lshl_or_b32 v4, v6, 2, v4
	s_lshl_b32 s33, s98, 5
	s_lshl_b32 s34, s74, 5
	s_mov_b32 s3, 0
	s_mov_b64 s[4:5], 0x400
	v_add_u32_e32 v12, 0x400, v1
	s_mov_b32 s35, s98
	s_branch .LBB0_163
